# four rounds of deferred weight items on G1's slack workgroups; only 112 items per layer left in MIX2
# speedup vs baseline: 1.0025x; 1.0005x over previous
.Lsc_g1:
	s_sub_i32 s55, s45, 223
	s_cmp_lt_i32 s55, 0
	s_cbranch_scc1 .Lsc_done
	s_lshl_b32 s55, s55, 3
	s_add_i32 s55, s55, s46
	s_movk_i32 s30, 264
	s_mul_i32 s69, s47, 0x1200
	s_add_i32 s64, s69, 0x7c0
	s_add_i32 s31, s69, 0xbe0
	s_branch .Lsc_wt_go

.Lsc_m2:
	s_sub_i32 s55, s45, 225
	s_cmp_lt_u32 s45, 225
	s_cbranch_scc1 .Lsc_done
	s_lshl_b32 s55, s55, 3
	s_add_i32 s55, s55, s46
	s_movk_i32 s30, 248
	s_mul_i32 s69, s47, 0x1200
	s_add_i32 s64, s69, 0xbe0
	s_add_i32 s31, s69, 0xc50
